# phase 5 only: scan workgroups take 2 prep pairs (ctx scan is half length), prep-only workgroups 2
# speedup vs baseline: 1.0029x; 1.0029x over previous
.LBB0_551:
	v_readlane_b32 s0, v255, 17
	v_readlane_b32 s2, v250, 0
	s_nop 3
	s_add_i32 s1, s0, 1
	v_writelane_b32 v255, s1, 17
	s_cmp_eq_u32 s10, 5
	s_cselect_b32 s22, 2, 3
	s_cmp_lt_u32 s2, 0x80
	s_cbranch_scc1 .Lps_b
	s_lshl_b32 s1, s0, 7
	s_add_i32 s1, s1, s2
	s_addk_i32 s1, 0xff80
	s_cmp_lt_u32 s0, s22
	s_branch .Lps_j
.Lps_b:
	s_lshl_b32 s1, s22, 7
	s_add_i32 s1, s1, s2
	s_lshl_b32 s23, s0, 7
	s_add_i32 s1, s1, s23
	s_sub_i32 s22, 4, s22
	s_cmp_lt_u32 s0, s22
